# v71 + layer-0 FFN-out epilogue stores its bf16 residual and h write-through (sc1) so the grid barrier before layer 1 has little left to write back
# baseline (speedup 1.0000x reference)
.LBB0_84:
	s_andn2_b64 vcc, exec, s[4:5]
	v_lshl_add_u64 v[114:115], s[70:71], 1, v[142:143]
	s_cbranch_vccnz .LBB0_86
	s_movk_i32 s4, 0x1600
	v_cvt_pk_bf16_f32 v124, v60, v61
	v_cvt_pk_bf16_f32 v125, v62, v63
	v_cvt_pk_bf16_f32 v126, v64, v65
	v_cvt_pk_bf16_f32 v127, v66, v67
	v_mad_i64_i32 v[158:159], s[4:5], v156, s4, v[114:115]
	global_store_dwordx4 v[158:159], v[124:127], off sc1

.LBB0_88:
	s_andn2_b64 vcc, exec, s[74:75]
	s_cbranch_vccnz .LBB0_90
	v_add_u32_e32 v0, s68, v169
	s_movk_i32 s8, 0x1600
	v_cvt_pk_bf16_f32 v124, v56, v57
	v_cvt_pk_bf16_f32 v125, v58, v59
	v_cvt_pk_bf16_f32 v126, v52, v53
	v_cvt_pk_bf16_f32 v127, v54, v55
	v_mad_i64_i32 v[110:111], s[74:75], v0, s8, v[114:115]
	global_store_dwordx4 v[110:111], v[124:127], off sc1

.LBB0_92:
	s_andn2_b64 vcc, exec, s[74:75]
	s_cbranch_vccnz .LBB0_94
	v_add_u32_e32 v0, s68, v170
	s_movk_i32 s8, 0x1600
	v_cvt_pk_bf16_f32 v124, v48, v49
	v_cvt_pk_bf16_f32 v125, v50, v51
	v_cvt_pk_bf16_f32 v126, v44, v45
	v_cvt_pk_bf16_f32 v127, v46, v47
	v_mad_i64_i32 v[106:107], s[74:75], v0, s8, v[114:115]
	global_store_dwordx4 v[106:107], v[124:127], off sc1

.LBB0_96:
	s_andn2_b64 vcc, exec, s[74:75]
	s_cbranch_vccnz .LBB0_98
	v_add_u32_e32 v0, s68, v171
	s_movk_i32 s8, 0x1600
	v_cvt_pk_bf16_f32 v120, v40, v41
	v_cvt_pk_bf16_f32 v121, v42, v43
	v_cvt_pk_bf16_f32 v122, v36, v37
	v_cvt_pk_bf16_f32 v123, v38, v39
	v_mad_i64_i32 v[102:103], s[74:75], v0, s8, v[114:115]
	global_store_dwordx4 v[102:103], v[120:123], off sc1

.LBB0_100:
	s_andn2_b64 vcc, exec, s[74:75]
	s_cbranch_vccnz .LBB0_102
	s_movk_i32 s8, 0x1600
	v_cvt_pk_bf16_f32 v84, v32, v33
	v_cvt_pk_bf16_f32 v85, v34, v35
	v_cvt_pk_bf16_f32 v86, v28, v29
	v_cvt_pk_bf16_f32 v87, v30, v31
	v_mad_i64_i32 v[92:93], s[74:75], v156, s8, v[114:115]
	global_store_dwordx4 v[92:93], v[84:87], off offset:16 sc1

.LBB0_104:
	s_andn2_b64 vcc, exec, s[74:75]
	s_cbranch_vccnz .LBB0_106
	v_add_u32_e32 v0, s68, v169
	s_movk_i32 s8, 0x1600
	v_cvt_pk_bf16_f32 v76, v24, v25
	v_cvt_pk_bf16_f32 v77, v26, v27
	v_cvt_pk_bf16_f32 v78, v20, v21
	v_cvt_pk_bf16_f32 v79, v22, v23
	v_mad_i64_i32 v[84:85], s[74:75], v0, s8, v[114:115]
	global_store_dwordx4 v[84:85], v[76:79], off offset:16 sc1

.LBB0_108:
	s_andn2_b64 vcc, exec, s[74:75]
	s_cbranch_vccnz .LBB0_110
	v_add_u32_e32 v0, s68, v170
	s_movk_i32 s8, 0x1600
	v_cvt_pk_bf16_f32 v72, v16, v17
	v_cvt_pk_bf16_f32 v73, v18, v19
	v_cvt_pk_bf16_f32 v74, v12, v13
	v_cvt_pk_bf16_f32 v75, v14, v15
	v_mad_i64_i32 v[76:77], s[74:75], v0, s8, v[114:115]
	global_store_dwordx4 v[76:77], v[72:75], off offset:16 sc1

.LBB0_115:
	v_add_u32_e32 v0, s68, v171
	s_movk_i32 s4, 0x1600
	v_cvt_pk_bf16_f32 v68, v8, v9
	v_cvt_pk_bf16_f32 v69, v10, v11
	v_cvt_pk_bf16_f32 v70, v4, v5
	v_cvt_pk_bf16_f32 v71, v6, v7
	v_mad_i64_i32 v[72:73], s[4:5], v0, s4, v[114:115]
	global_store_dwordx4 v[72:73], v[68:71], off offset:16 sc1
	s_andn2_b64 vcc, exec, s[56:57]
	s_cbranch_vccnz .LBB0_113

.LBB0_146:
	s_or_b64 exec, exec, s[42:43]
	s_waitcnt lgkmcnt(0)
	s_barrier
	ds_read_b32 v2, v174
	s_waitcnt vmcnt(11)
	v_pk_add_f32 v[110:111], v[110:111], 1.0 op_sel_hi:[1,0]
	v_pk_add_f32 v[108:109], v[108:109], 1.0 op_sel_hi:[1,0]
	s_waitcnt vmcnt(9)
	v_pk_mul_f32 v[102:103], v[102:103], v[110:111]
	v_pk_mul_f32 v[100:101], v[100:101], v[108:109]
	s_waitcnt vmcnt(1)
	v_pk_add_f32 v[108:109], v[114:115], 1.0 op_sel_hi:[1,0]
	v_pk_add_f32 v[110:111], v[112:113], 1.0 op_sel_hi:[1,0]
	v_pk_mul_f32 v[108:109], v[90:91], v[108:109]
	v_pk_mul_f32 v[110:111], v[88:89], v[110:111]
	v_pk_add_f32 v[88:89], v[106:107], 1.0 op_sel_hi:[1,0]
	v_pk_add_f32 v[90:91], v[104:105], 1.0 op_sel_hi:[1,0]
	v_pk_mul_f32 v[88:89], v[94:95], v[88:89]
	v_pk_mul_f32 v[90:91], v[92:93], v[90:91]
	v_pk_add_f32 v[92:93], v[98:99], 1.0 op_sel_hi:[1,0]
	v_pk_add_f32 v[94:95], v[96:97], 1.0 op_sel_hi:[1,0]
	ds_read_b32 v96, v175
	ds_read_b32 v98, v176
	ds_read_b32 v104, v177
	s_waitcnt lgkmcnt(3)
	v_pk_mul_f32 v[62:63], v[62:63], v[2:3] op_sel_hi:[1,0]
	v_pk_mul_f32 v[60:61], v[60:61], v[2:3] op_sel_hi:[1,0]
	v_pk_fma_f32 v[62:63], v[102:103], v[62:63], v[78:79]
	v_pk_fma_f32 v[60:61], v[100:101], v[60:61], v[76:77]
	v_pk_mul_f32 v[64:65], v[64:65], v[2:3] op_sel_hi:[1,0]
	v_cvt_pk_bf16_f32 v60, v60, v61
	v_cvt_pk_bf16_f32 v61, v62, v63
	v_pk_mul_f32 v[62:63], v[66:67], v[2:3] op_sel_hi:[1,0]
	v_pk_mul_f32 v[86:87], v[86:87], v[92:93]
	v_pk_fma_f32 v[66:67], v[108:109], v[62:63], v[82:83]
	v_pk_fma_f32 v[62:63], v[110:111], v[64:65], v[80:81]
	v_lshl_add_u64 v[92:93], s[70:71], 1, v[144:145]
	v_cvt_pk_bf16_f32 v62, v62, v63
	v_cvt_pk_bf16_f32 v63, v66, v67
	s_waitcnt lgkmcnt(2)
	v_pk_mul_f32 v[58:59], v[58:59], v[96:97] op_sel_hi:[1,0]
	v_pk_mul_f32 v[56:57], v[56:57], v[96:97] op_sel_hi:[1,0]
	v_pk_mul_f32 v[52:53], v[52:53], v[96:97] op_sel_hi:[1,0]
	s_waitcnt lgkmcnt(1)
	v_pk_mul_f32 v[50:51], v[50:51], v[98:99] op_sel_hi:[1,0]
	v_pk_mul_f32 v[48:49], v[48:49], v[98:99] op_sel_hi:[1,0]
	v_pk_mul_f32 v[44:45], v[44:45], v[98:99] op_sel_hi:[1,0]
	v_pk_mul_f32 v[84:85], v[84:85], v[94:95]
	v_lshl_add_u64 v[94:95], v[92:93], 0, v[146:147]
	v_permlane16_swap_b32_e32 v60, v62
	v_permlane16_swap_b32_e32 v61, v63
	v_pk_fma_f32 v[58:59], v[102:103], v[58:59], v[78:79]
	v_pk_fma_f32 v[56:57], v[100:101], v[56:57], v[76:77]
	v_pk_fma_f32 v[52:53], v[110:111], v[52:53], v[80:81]
	v_pk_fma_f32 v[50:51], v[102:103], v[50:51], v[78:79]
	v_pk_fma_f32 v[48:49], v[100:101], v[48:49], v[76:77]
	v_pk_fma_f32 v[44:45], v[110:111], v[44:45], v[80:81]
	global_store_dwordx4 v[94:95], v[60:63], off sc1
	v_cvt_pk_bf16_f32 v56, v56, v57
	v_cvt_pk_bf16_f32 v57, v58, v59
	v_add_u32_e32 v60, s68, v169
	v_pk_mul_f32 v[54:55], v[54:55], v[96:97] op_sel_hi:[1,0]
	v_cvt_pk_bf16_f32 v58, v52, v53
	v_add_u32_e32 v52, s68, v170
	v_cvt_pk_bf16_f32 v48, v48, v49
	v_cvt_pk_bf16_f32 v49, v50, v51
	v_pk_mul_f32 v[46:47], v[46:47], v[98:99] op_sel_hi:[1,0]
	v_cvt_pk_bf16_f32 v50, v44, v45
	v_add_u32_e32 v44, s68, v171
	s_waitcnt lgkmcnt(0)
	v_pk_mul_f32 v[42:43], v[42:43], v[104:105] op_sel_hi:[1,0]
	v_pk_mul_f32 v[40:41], v[40:41], v[104:105] op_sel_hi:[1,0]
	v_pk_mul_f32 v[38:39], v[38:39], v[104:105] op_sel_hi:[1,0]
	v_pk_mul_f32 v[36:37], v[36:37], v[104:105] op_sel_hi:[1,0]
	v_pk_mul_f32 v[34:35], v[34:35], v[2:3] op_sel_hi:[1,0]
	v_pk_mul_f32 v[32:33], v[32:33], v[2:3] op_sel_hi:[1,0]
	v_pk_mul_f32 v[30:31], v[30:31], v[2:3] op_sel_hi:[1,0]
	v_pk_mul_f32 v[28:29], v[28:29], v[2:3] op_sel_hi:[1,0]
	v_pk_mul_f32 v[26:27], v[26:27], v[96:97] op_sel_hi:[1,0]
	v_pk_mul_f32 v[24:25], v[24:25], v[96:97] op_sel_hi:[1,0]
	v_pk_mul_f32 v[22:23], v[22:23], v[96:97] op_sel_hi:[1,0]
	v_pk_mul_f32 v[20:21], v[20:21], v[96:97] op_sel_hi:[1,0]
	v_pk_mul_f32 v[18:19], v[18:19], v[98:99] op_sel_hi:[1,0]
	v_pk_mul_f32 v[16:17], v[16:17], v[98:99] op_sel_hi:[1,0]
	v_pk_mul_f32 v[14:15], v[14:15], v[98:99] op_sel_hi:[1,0]
	v_pk_mul_f32 v[12:13], v[12:13], v[98:99] op_sel_hi:[1,0]
	v_pk_mul_f32 v[10:11], v[10:11], v[104:105] op_sel_hi:[1,0]
	v_pk_mul_f32 v[8:9], v[8:9], v[104:105] op_sel_hi:[1,0]
	v_pk_mul_f32 v[6:7], v[6:7], v[104:105] op_sel_hi:[1,0]
	v_pk_mul_f32 v[4:5], v[4:5], v[104:105] op_sel_hi:[1,0]
	v_ashrrev_i32_e32 v61, 31, v60
	v_pk_fma_f32 v[54:55], v[108:109], v[54:55], v[82:83]
	v_ashrrev_i32_e32 v53, 31, v52
	v_pk_fma_f32 v[46:47], v[108:109], v[46:47], v[82:83]
	v_ashrrev_i32_e32 v45, 31, v44
	v_pk_fma_f32 v[42:43], v[102:103], v[42:43], v[78:79]
	v_pk_fma_f32 v[40:41], v[100:101], v[40:41], v[76:77]
	v_pk_fma_f32 v[38:39], v[108:109], v[38:39], v[82:83]
	v_pk_fma_f32 v[36:37], v[110:111], v[36:37], v[80:81]
	v_pk_fma_f32 v[34:35], v[88:89], v[34:35], v[74:75]
	v_pk_fma_f32 v[32:33], v[90:91], v[32:33], v[72:73]
	s_waitcnt vmcnt(1)
	v_pk_fma_f32 v[30:31], v[86:87], v[30:31], v[70:71]
	v_pk_fma_f32 v[28:29], v[84:85], v[28:29], v[68:69]
	v_pk_fma_f32 v[26:27], v[88:89], v[26:27], v[74:75]
	v_pk_fma_f32 v[24:25], v[90:91], v[24:25], v[72:73]
	v_pk_fma_f32 v[22:23], v[86:87], v[22:23], v[70:71]
	v_pk_fma_f32 v[20:21], v[84:85], v[20:21], v[68:69]
	v_pk_fma_f32 v[18:19], v[88:89], v[18:19], v[74:75]
	v_pk_fma_f32 v[16:17], v[90:91], v[16:17], v[72:73]
	v_pk_fma_f32 v[14:15], v[86:87], v[14:15], v[70:71]
	v_pk_fma_f32 v[12:13], v[84:85], v[12:13], v[68:69]
	v_pk_fma_f32 v[10:11], v[88:89], v[10:11], v[74:75]
	v_pk_fma_f32 v[8:9], v[90:91], v[8:9], v[72:73]
	v_pk_fma_f32 v[6:7], v[86:87], v[6:7], v[70:71]
	v_pk_fma_f32 v[4:5], v[84:85], v[4:5], v[68:69]
	v_lshlrev_b64 v[60:61], 11, v[60:61]
	v_cvt_pk_bf16_f32 v59, v54, v55
	v_lshlrev_b64 v[52:53], 11, v[52:53]
	v_cvt_pk_bf16_f32 v51, v46, v47
	v_lshlrev_b64 v[44:45], 11, v[44:45]
	v_cvt_pk_bf16_f32 v40, v40, v41
	v_cvt_pk_bf16_f32 v41, v42, v43
	v_cvt_pk_bf16_f32 v42, v36, v37
	v_cvt_pk_bf16_f32 v43, v38, v39
	v_cvt_pk_bf16_f32 v32, v32, v33
	v_cvt_pk_bf16_f32 v33, v34, v35
	v_cvt_pk_bf16_f32 v34, v28, v29
	v_cvt_pk_bf16_f32 v35, v30, v31
	v_cvt_pk_bf16_f32 v24, v24, v25
	v_cvt_pk_bf16_f32 v25, v26, v27
	v_cvt_pk_bf16_f32 v26, v20, v21
	v_cvt_pk_bf16_f32 v27, v22, v23
	v_cvt_pk_bf16_f32 v16, v16, v17
	v_cvt_pk_bf16_f32 v17, v18, v19
	v_cvt_pk_bf16_f32 v18, v12, v13
	v_cvt_pk_bf16_f32 v19, v14, v15
	v_cvt_pk_bf16_f32 v8, v8, v9
	v_cvt_pk_bf16_f32 v9, v10, v11
	v_cvt_pk_bf16_f32 v10, v4, v5
	v_cvt_pk_bf16_f32 v11, v6, v7
	v_lshl_add_u64 v[60:61], v[92:93], 0, v[60:61]
	v_permlane16_swap_b32_e32 v56, v58
	v_permlane16_swap_b32_e32 v57, v59
	v_lshl_add_u64 v[52:53], v[92:93], 0, v[52:53]
	v_permlane16_swap_b32_e32 v48, v50
	v_permlane16_swap_b32_e32 v49, v51
	v_lshl_add_u64 v[44:45], v[92:93], 0, v[44:45]
	v_permlane16_swap_b32_e32 v40, v42
	v_permlane16_swap_b32_e32 v41, v43
	v_permlane16_swap_b32_e32 v32, v34
	v_permlane16_swap_b32_e32 v33, v35
	v_permlane16_swap_b32_e32 v24, v26
	v_permlane16_swap_b32_e32 v25, v27
	v_permlane16_swap_b32_e32 v16, v18
	v_permlane16_swap_b32_e32 v17, v19
	v_permlane16_swap_b32_e32 v8, v10
	v_permlane16_swap_b32_e32 v9, v11
	global_store_dwordx4 v[60:61], v[56:59], off sc1
	global_store_dwordx4 v[52:53], v[48:51], off sc1
	global_store_dwordx4 v[44:45], v[40:43], off sc1
	global_store_dwordx4 v[94:95], v[32:35], off offset:256 sc1
	global_store_dwordx4 v[60:61], v[24:27], off offset:256 sc1
	global_store_dwordx4 v[52:53], v[16:19], off offset:256 sc1
	global_store_dwordx4 v[44:45], v[8:11], off offset:256 sc1
	s_andn2_b64 vcc, exec, s[64:65]
	s_mov_b64 s[4:5], -1
	s_cbranch_vccnz .LBB0_38
